# FFN-in: two A1 fragments pre-read one phase early into spare VGPRs v[244:251] (L3/L7 read 6 instead of 8), on top of early-invalidate barrier
# speedup vs baseline: 1.0286x; 1.0004x over previous
.LBB0_556:
	v_mov_b64_e32 v[0:1], 0x420
	s_ashr_i32 s49, s48, 31
	v_cmp_lt_i64_e32 vcc, s[50:51], v[0:1]
	s_lshl_b64 s[50:51], s[48:49], 19
	s_add_u32 s50, s4, s50
	s_addc_u32 s51, s5, s51
	s_and_b64 s[52:53], vcc, exec
	s_cselect_b32 s49, s51, s59
	s_cselect_b32 s67, s50, s58
	s_ashr_i32 s47, s46, 31
	s_lshl_b64 s[52:53], s[46:47], 19
	s_add_u32 s52, s10, s52
	s_addc_u32 s53, s11, s53
	s_and_b64 s[62:63], vcc, exec
	s_cselect_b32 s47, s53, s61
	s_cselect_b32 s68, s52, s60
	s_add_u32 s58, s58, 0x40080
	s_addc_u32 s59, s59, 0
	s_add_u32 s69, s60, 0x100
	s_addc_u32 s70, s61, 0
	s_mov_b32 s71, -2
	v_add_u32_e32 v96, 0x10000, v193
	ds_read_b128 v[80:83], v96
	ds_read_b128 v[88:91], v96 offset:1024
	ds_read_b128 v[102:105], v96 offset:2048
	ds_read_b128 v[106:109], v96 offset:3072
	s_add_u32 s60, s58, 0xfffc0080
	s_addc_u32 s61, s59, -1
	s_add_i32 s72, 0, 0x10000
	v_add_u32_e32 v96, s72, v193
	s_cmp_eq_u32 s71, 12
	s_cselect_b32 s63, s49, s61
	s_cselect_b32 s62, s67, s60
	s_cselect_b32 s61, s47, s70
	s_cselect_b32 s60, s68, s69
	s_add_i32 m0, s27, 0xc000
	ds_read_b128 v[160:163], v195
	ds_read_b128 v[164:167], v195 offset:1024
	ds_read_b128 v[168:171], v195 offset:2048
	ds_read_b128 v[172:175], v195 offset:3072
	ds_read_b128 v[182:185], v195 offset:4096
	ds_read_b128 v[186:189], v195 offset:5120
	ds_read_b128 v[196:199], v195 offset:6144
	ds_read_b128 v[200:203], v195 offset:7168
	global_load_lds_dwordx4 v156, s[58:59]
	s_add_i32 m0, s27, 0xe000
	s_nop 0
	global_load_lds_dwordx4 v158, s[58:59]
	s_setprio 1
	s_barrier
	s_waitcnt lgkmcnt(0)
	v_mfma_f32_16x16x32_bf16 v[142:145], v[80:83], v[160:163], 0
	v_mfma_f32_16x16x32_bf16 v[138:141], v[102:105], v[160:163], 0
	v_mfma_f32_16x16x32_bf16 v[126:129], v[80:83], v[168:171], 0
	v_mfma_f32_16x16x32_bf16 v[122:125], v[102:105], v[168:171], 0
	v_mfma_f32_16x16x32_bf16 v[110:113], v[80:83], v[182:185], 0
	v_mfma_f32_16x16x32_bf16 v[98:101], v[102:105], v[182:185], 0
	v_mfma_f32_16x16x32_bf16 v[76:79], v[80:83], v[196:199], 0
	v_mfma_f32_16x16x32_bf16 v[72:75], v[102:105], v[196:199], 0
	v_mfma_f32_16x16x32_bf16 v[142:145], v[88:91], v[164:167], v[142:145]
	v_mfma_f32_16x16x32_bf16 v[138:141], v[106:109], v[164:167], v[138:141]
	v_mfma_f32_16x16x32_bf16 v[126:129], v[88:91], v[172:175], v[126:129]
	v_mfma_f32_16x16x32_bf16 v[122:125], v[106:109], v[172:175], v[122:125]
	v_mfma_f32_16x16x32_bf16 v[110:113], v[88:91], v[186:189], v[110:113]
	v_mfma_f32_16x16x32_bf16 v[98:101], v[106:109], v[186:189], v[98:101]
	v_mfma_f32_16x16x32_bf16 v[76:79], v[88:91], v[200:203], v[76:79]
	v_mfma_f32_16x16x32_bf16 v[72:75], v[106:109], v[200:203], v[72:75]
	s_barrier
	s_setprio 0
	s_add_i32 s76, 0, 0x14000
	s_add_i32 s72, s72, s18
	v_add_u32_e32 v96, s76, v193
	v_lshl_add_u64 v[176:177], s[60:61], 0, v[150:151]
	s_mov_b32 m0, s72
	ds_read_b128 v[224:227], v96
	ds_read_b128 v[228:231], v96 offset:1024
	ds_read_b128 v[232:235], v96 offset:2048
	ds_read_b128 v[236:239], v96 offset:3072
	ds_read_b128 v[244:247], v195 offset:16384
	ds_read_b128 v[248:251], v195 offset:17408
	global_load_lds_dwordx4 v150, s[60:61]
	v_lshl_add_u64 v[190:191], s[60:61], 0, v[146:147]
	s_add_i32 m0, s72, 0x2000
	s_nop 0
	global_load_lds_dwordx4 v146, s[60:61]
	s_setprio 1
	s_barrier
	s_waitcnt lgkmcnt(0)
	v_mfma_f32_16x16x32_bf16 v[134:137], v[224:227], v[160:163], 0
	v_mfma_f32_16x16x32_bf16 v[130:133], v[232:235], v[160:163], 0
	v_mfma_f32_16x16x32_bf16 v[118:121], v[224:227], v[168:171], 0
	s_mov_b32 m0, s27
	v_mfma_f32_16x16x32_bf16 v[114:117], v[232:235], v[168:171], 0
	v_lshl_add_u64 v[240:241], s[62:63], 0, v[152:153]
	v_mfma_f32_16x16x32_bf16 v[92:95], v[224:227], v[182:185], 0
	v_mfma_f32_16x16x32_bf16 v[84:87], v[232:235], v[182:185], 0
	v_mfma_f32_16x16x32_bf16 v[68:71], v[224:227], v[196:199], 0
	v_mfma_f32_16x16x32_bf16 v[64:67], v[232:235], v[196:199], 0
	v_mfma_f32_16x16x32_bf16 v[134:137], v[228:231], v[164:167], v[134:137]
	v_mfma_f32_16x16x32_bf16 v[130:133], v[236:239], v[164:167], v[130:133]
	v_mfma_f32_16x16x32_bf16 v[118:121], v[228:231], v[172:175], v[118:121]
	v_mfma_f32_16x16x32_bf16 v[114:117], v[236:239], v[172:175], v[114:117]
	v_mfma_f32_16x16x32_bf16 v[92:95], v[228:231], v[186:189], v[92:95]
	v_mfma_f32_16x16x32_bf16 v[84:87], v[236:239], v[186:189], v[84:87]
	v_mfma_f32_16x16x32_bf16 v[68:71], v[228:231], v[200:203], v[68:71]
	v_mfma_f32_16x16x32_bf16 v[64:67], v[236:239], v[200:203], v[64:67]
	s_barrier
	s_setprio 0
	ds_read_b128 v[168:171], v195 offset:18432
	ds_read_b128 v[172:175], v195 offset:19456
	ds_read_b128 v[182:185], v195 offset:20480
	ds_read_b128 v[186:189], v195 offset:21504
	ds_read_b128 v[196:199], v195 offset:22528
	ds_read_b128 v[200:203], v195 offset:23552
	global_load_lds_dwordx4 v152, s[62:63]
	v_lshl_add_u64 v[242:243], s[62:63], 0, v[148:149]
	s_mov_b32 m0, s28
	s_nop 0
	global_load_lds_dwordx4 v148, s[62:63]
	s_waitcnt vmcnt(10)
	s_setprio 1
	s_barrier
	s_waitcnt lgkmcnt(0)
	v_mfma_f32_16x16x32_bf16 v[60:63], v[80:83], v[244:247], 0
	v_mfma_f32_16x16x32_bf16 v[56:59], v[102:105], v[244:247], 0
	v_mfma_f32_16x16x32_bf16 v[44:47], v[80:83], v[168:171], 0
	v_mfma_f32_16x16x32_bf16 v[40:43], v[102:105], v[168:171], 0
	v_mfma_f32_16x16x32_bf16 v[28:31], v[80:83], v[182:185], 0
	v_mfma_f32_16x16x32_bf16 v[24:27], v[102:105], v[182:185], 0
	v_mfma_f32_16x16x32_bf16 v[12:15], v[80:83], v[196:199], 0
	v_mfma_f32_16x16x32_bf16 v[8:11], v[102:105], v[196:199], 0
	v_mfma_f32_16x16x32_bf16 v[60:63], v[88:91], v[248:251], v[60:63]
	v_mfma_f32_16x16x32_bf16 v[56:59], v[106:109], v[248:251], v[56:59]
	v_mfma_f32_16x16x32_bf16 v[44:47], v[88:91], v[172:175], v[44:47]
	v_mfma_f32_16x16x32_bf16 v[40:43], v[106:109], v[172:175], v[40:43]
	v_mfma_f32_16x16x32_bf16 v[28:31], v[88:91], v[186:189], v[28:31]
	v_mfma_f32_16x16x32_bf16 v[24:27], v[106:109], v[186:189], v[24:27]
	v_mfma_f32_16x16x32_bf16 v[12:15], v[88:91], v[200:203], v[12:15]
	v_mfma_f32_16x16x32_bf16 v[8:11], v[106:109], v[200:203], v[8:11]
	s_barrier
	s_setprio 0
	v_add_u32_e32 v96, 0x18000, v193
	ds_read_b128 v[80:83], v96
	ds_read_b128 v[88:91], v96 offset:1024
	ds_read_b128 v[102:105], v96 offset:2048
	ds_read_b128 v[106:109], v96 offset:3072
	s_add_u32 s74, s60, 0x40000
	s_addc_u32 s75, s61, 0
	s_add_i32 s72, s76, s18
	s_mov_b32 m0, s72
	s_nop 0
	global_load_lds_dwordx4 v150, s[74:75]
	s_add_i32 m0, s72, 0x2000
	s_nop 0
	global_load_lds_dwordx4 v146, s[74:75]
	s_waitcnt vmcnt(6)
	s_setprio 1
	s_barrier
	v_mfma_f32_16x16x32_bf16 v[52:55], v[224:227], v[244:247], 0
	v_mfma_f32_16x16x32_bf16 v[48:51], v[232:235], v[244:247], 0
	v_mfma_f32_16x16x32_bf16 v[36:39], v[224:227], v[168:171], 0
	s_add_i32 s72, 0, 0x18000
	v_mfma_f32_16x16x32_bf16 v[32:35], v[232:235], v[168:171], 0
	v_add_u32_e32 v96, s72, v193
	v_mfma_f32_16x16x32_bf16 v[20:23], v[224:227], v[182:185], 0
	v_mfma_f32_16x16x32_bf16 v[16:19], v[232:235], v[182:185], 0
	v_mfma_f32_16x16x32_bf16 v[4:7], v[224:227], v[196:199], 0
	v_mfma_f32_16x16x32_bf16 v[0:3], v[232:235], v[196:199], 0
	v_mfma_f32_16x16x32_bf16 v[52:55], v[228:231], v[248:251], v[52:55]
	v_mfma_f32_16x16x32_bf16 v[48:51], v[236:239], v[248:251], v[48:51]
	v_mfma_f32_16x16x32_bf16 v[36:39], v[228:231], v[172:175], v[36:39]
	v_mfma_f32_16x16x32_bf16 v[32:35], v[236:239], v[172:175], v[32:35]
	v_mfma_f32_16x16x32_bf16 v[20:23], v[228:231], v[186:189], v[20:23]
	v_mfma_f32_16x16x32_bf16 v[16:19], v[236:239], v[186:189], v[16:19]
	v_mfma_f32_16x16x32_bf16 v[4:7], v[228:231], v[200:203], v[4:7]
	v_mfma_f32_16x16x32_bf16 v[0:3], v[236:239], v[200:203], v[0:3]
	s_barrier
	s_setprio 0
	s_add_u32 s62, s62, 0x40000
	s_addc_u32 s63, s63, 0
	s_mov_b32 m0, s37
	ds_read_b128 v[160:163], v195 offset:32768
	ds_read_b128 v[164:167], v195 offset:33792
	ds_read_b128 v[168:171], v195 offset:34816
	ds_read_b128 v[172:175], v195 offset:35840
	ds_read_b128 v[182:185], v195 offset:36864
	ds_read_b128 v[186:189], v195 offset:37888
	ds_read_b128 v[196:199], v195 offset:38912
	ds_read_b128 v[200:203], v195 offset:39936
	global_load_lds_dwordx4 v152, s[62:63]
	s_mov_b32 m0, s56
	s_nop 0
	global_load_lds_dwordx4 v148, s[62:63]
	s_setprio 1
	s_barrier
	s_waitcnt lgkmcnt(0)
	v_mfma_f32_16x16x32_bf16 v[142:145], v[80:83], v[160:163], v[142:145]
	v_mfma_f32_16x16x32_bf16 v[138:141], v[102:105], v[160:163], v[138:141]
	v_mfma_f32_16x16x32_bf16 v[126:129], v[80:83], v[168:171], v[126:129]
	v_mfma_f32_16x16x32_bf16 v[122:125], v[102:105], v[168:171], v[122:125]
	v_mfma_f32_16x16x32_bf16 v[110:113], v[80:83], v[182:185], v[110:113]
	v_mfma_f32_16x16x32_bf16 v[98:101], v[102:105], v[182:185], v[98:101]
	v_mfma_f32_16x16x32_bf16 v[76:79], v[80:83], v[196:199], v[76:79]
	v_mfma_f32_16x16x32_bf16 v[72:75], v[102:105], v[196:199], v[72:75]
	v_mfma_f32_16x16x32_bf16 v[142:145], v[88:91], v[164:167], v[142:145]
	v_mfma_f32_16x16x32_bf16 v[138:141], v[106:109], v[164:167], v[138:141]
	v_mfma_f32_16x16x32_bf16 v[126:129], v[88:91], v[172:175], v[126:129]
	v_mfma_f32_16x16x32_bf16 v[122:125], v[106:109], v[172:175], v[122:125]
	v_mfma_f32_16x16x32_bf16 v[110:113], v[88:91], v[186:189], v[110:113]
	v_mfma_f32_16x16x32_bf16 v[98:101], v[106:109], v[186:189], v[98:101]
	v_mfma_f32_16x16x32_bf16 v[76:79], v[88:91], v[200:203], v[76:79]
	v_mfma_f32_16x16x32_bf16 v[72:75], v[106:109], v[200:203], v[72:75]
	s_barrier
	s_setprio 0
	s_add_i32 s62, 0, 0x1c000
	s_add_i32 s63, s72, s18
	v_add_u32_e32 v96, s62, v193
	v_lshl_add_u64 v[176:177], v[176:177], 0, s[6:7]
	s_mov_b32 m0, s63
	ds_read_b128 v[224:227], v96
	ds_read_b128 v[228:231], v96 offset:1024
	ds_read_b128 v[232:235], v96 offset:2048
	ds_read_b128 v[236:239], v96 offset:3072
	ds_read_b128 v[244:247], v195 offset:49152
	ds_read_b128 v[248:251], v195 offset:50176
	global_load_lds_dwordx4 v[176:177], off
	v_lshl_add_u64 v[176:177], v[190:191], 0, s[6:7]
	s_add_i32 m0, s63, 0x2000
	s_nop 0
	global_load_lds_dwordx4 v[176:177], off
	s_setprio 1
	s_barrier
	s_waitcnt lgkmcnt(0)
	v_mfma_f32_16x16x32_bf16 v[134:137], v[224:227], v[160:163], v[134:137]
	v_mfma_f32_16x16x32_bf16 v[130:133], v[232:235], v[160:163], v[130:133]
	v_mfma_f32_16x16x32_bf16 v[118:121], v[224:227], v[168:171], v[118:121]
	s_mov_b32 m0, s64
	v_mfma_f32_16x16x32_bf16 v[114:117], v[232:235], v[168:171], v[114:117]
	v_lshl_add_u64 v[176:177], v[240:241], 0, s[6:7]
	v_mfma_f32_16x16x32_bf16 v[92:95], v[224:227], v[182:185], v[92:95]
	v_mfma_f32_16x16x32_bf16 v[84:87], v[232:235], v[182:185], v[84:87]
	v_mfma_f32_16x16x32_bf16 v[68:71], v[224:227], v[196:199], v[68:71]
	v_mfma_f32_16x16x32_bf16 v[64:67], v[232:235], v[196:199], v[64:67]
	v_mfma_f32_16x16x32_bf16 v[134:137], v[228:231], v[164:167], v[134:137]
	v_mfma_f32_16x16x32_bf16 v[130:133], v[236:239], v[164:167], v[130:133]
	v_mfma_f32_16x16x32_bf16 v[118:121], v[228:231], v[172:175], v[118:121]
	v_mfma_f32_16x16x32_bf16 v[114:117], v[236:239], v[172:175], v[114:117]
	v_mfma_f32_16x16x32_bf16 v[92:95], v[228:231], v[186:189], v[92:95]
	v_mfma_f32_16x16x32_bf16 v[84:87], v[236:239], v[186:189], v[84:87]
	v_mfma_f32_16x16x32_bf16 v[68:71], v[228:231], v[200:203], v[68:71]
	v_mfma_f32_16x16x32_bf16 v[64:67], v[236:239], v[200:203], v[64:67]
	s_barrier
	s_setprio 0
	ds_read_b128 v[168:171], v195 offset:51200
	ds_read_b128 v[172:175], v195 offset:52224
	ds_read_b128 v[182:185], v195 offset:53248
	ds_read_b128 v[186:189], v195 offset:54272
	ds_read_b128 v[196:199], v195 offset:55296
	ds_read_b128 v[200:203], v195 offset:56320
	global_load_lds_dwordx4 v[176:177], off
	v_lshl_add_u64 v[176:177], v[242:243], 0, s[6:7]
	s_mov_b32 m0, s65
	s_nop 0
	global_load_lds_dwordx4 v[176:177], off
	s_waitcnt vmcnt(10)
	s_setprio 1
	s_barrier
	s_waitcnt lgkmcnt(0)
	v_mfma_f32_16x16x32_bf16 v[60:63], v[80:83], v[244:247], v[60:63]
	v_mfma_f32_16x16x32_bf16 v[56:59], v[102:105], v[244:247], v[56:59]
	v_mfma_f32_16x16x32_bf16 v[44:47], v[80:83], v[168:171], v[44:47]
	v_mfma_f32_16x16x32_bf16 v[40:43], v[102:105], v[168:171], v[40:43]
	v_mfma_f32_16x16x32_bf16 v[28:31], v[80:83], v[182:185], v[28:31]
	v_mfma_f32_16x16x32_bf16 v[24:27], v[102:105], v[182:185], v[24:27]
	v_mfma_f32_16x16x32_bf16 v[12:15], v[80:83], v[196:199], v[12:15]
	v_mfma_f32_16x16x32_bf16 v[8:11], v[102:105], v[196:199], v[8:11]
	v_mfma_f32_16x16x32_bf16 v[60:63], v[88:91], v[248:251], v[60:63]
	v_mfma_f32_16x16x32_bf16 v[56:59], v[106:109], v[248:251], v[56:59]
	v_mfma_f32_16x16x32_bf16 v[44:47], v[88:91], v[172:175], v[44:47]
	v_mfma_f32_16x16x32_bf16 v[40:43], v[106:109], v[172:175], v[40:43]
	v_mfma_f32_16x16x32_bf16 v[28:31], v[88:91], v[186:189], v[28:31]
	v_mfma_f32_16x16x32_bf16 v[24:27], v[106:109], v[186:189], v[24:27]
	v_mfma_f32_16x16x32_bf16 v[12:15], v[88:91], v[200:203], v[12:15]
	v_mfma_f32_16x16x32_bf16 v[8:11], v[106:109], v[200:203], v[8:11]
	s_barrier
	s_setprio 0
	v_add_u32_e32 v96, 0x10000, v193
	ds_read_b128 v[80:83], v96
	ds_read_b128 v[88:91], v96 offset:1024
	ds_read_b128 v[102:105], v96 offset:2048
	ds_read_b128 v[106:109], v96 offset:3072
	s_add_u32 s60, s60, 0x40080
	s_addc_u32 s61, s61, 0
	s_add_i32 s62, s62, s18
	s_mov_b32 m0, s62
	s_nop 0
	global_load_lds_dwordx4 v150, s[60:61]
	s_add_i32 m0, s62, 0x2000
	s_nop 0
	global_load_lds_dwordx4 v146, s[60:61]
	s_waitcnt vmcnt(6)
	s_setprio 1
	s_barrier
	v_mfma_f32_16x16x32_bf16 v[52:55], v[224:227], v[244:247], v[52:55]
	v_mfma_f32_16x16x32_bf16 v[48:51], v[232:235], v[244:247], v[48:51]
	v_mfma_f32_16x16x32_bf16 v[36:39], v[224:227], v[168:171], v[36:39]
	s_add_i32 s71, s71, 2
	v_mfma_f32_16x16x32_bf16 v[32:35], v[232:235], v[168:171], v[32:35]
	s_add_u32 s58, s58, 0x100
	v_mfma_f32_16x16x32_bf16 v[20:23], v[224:227], v[182:185], v[20:23]
	s_addc_u32 s59, s59, 0
	v_mfma_f32_16x16x32_bf16 v[16:19], v[232:235], v[182:185], v[16:19]
	s_add_u32 s69, s69, 0x100
	v_mfma_f32_16x16x32_bf16 v[4:7], v[224:227], v[196:199], v[4:7]
	s_addc_u32 s70, s70, 0
	v_mfma_f32_16x16x32_bf16 v[0:3], v[232:235], v[196:199], v[0:3]
	s_cmp_gt_u32 s71, 13
	v_mfma_f32_16x16x32_bf16 v[52:55], v[228:231], v[248:251], v[52:55]
	v_mfma_f32_16x16x32_bf16 v[48:51], v[236:239], v[248:251], v[48:51]
	v_mfma_f32_16x16x32_bf16 v[36:39], v[228:231], v[172:175], v[36:39]
	v_mfma_f32_16x16x32_bf16 v[32:35], v[236:239], v[172:175], v[32:35]
	v_mfma_f32_16x16x32_bf16 v[20:23], v[228:231], v[186:189], v[20:23]
	v_mfma_f32_16x16x32_bf16 v[16:19], v[236:239], v[186:189], v[16:19]
	v_mfma_f32_16x16x32_bf16 v[4:7], v[228:231], v[200:203], v[4:7]
	v_mfma_f32_16x16x32_bf16 v[0:3], v[236:239], v[200:203], v[0:3]
	s_barrier
	s_setprio 0
.LBB0_557:
	s_add_u32 s60, s58, 0xfffc0080
	s_addc_u32 s61, s59, -1
	s_add_i32 s72, 0, 0x10000
	v_add_u32_e32 v96, s72, v193
	s_cmp_eq_u32 s71, 12
	s_cselect_b32 s63, s49, s61
	s_cselect_b32 s62, s67, s60
	s_cselect_b32 s61, s47, s70
	s_cselect_b32 s60, s68, s69
	s_add_i32 m0, s27, 0xc000
	ds_read_b128 v[160:163], v195
	ds_read_b128 v[164:167], v195 offset:1024
	ds_read_b128 v[168:171], v195 offset:2048
	ds_read_b128 v[172:175], v195 offset:3072
	ds_read_b128 v[182:185], v195 offset:4096
	ds_read_b128 v[186:189], v195 offset:5120
	ds_read_b128 v[196:199], v195 offset:6144
	ds_read_b128 v[200:203], v195 offset:7168
	global_load_lds_dwordx4 v156, s[58:59]
	s_add_i32 m0, s27, 0xe000
	s_nop 0
	global_load_lds_dwordx4 v158, s[58:59]
	s_setprio 1
	s_barrier
	s_waitcnt lgkmcnt(0)
	v_mfma_f32_16x16x32_bf16 v[142:145], v[80:83], v[160:163], v[142:145]
	v_mfma_f32_16x16x32_bf16 v[138:141], v[102:105], v[160:163], v[138:141]
	v_mfma_f32_16x16x32_bf16 v[126:129], v[80:83], v[168:171], v[126:129]
	v_mfma_f32_16x16x32_bf16 v[122:125], v[102:105], v[168:171], v[122:125]
	v_mfma_f32_16x16x32_bf16 v[110:113], v[80:83], v[182:185], v[110:113]
	v_mfma_f32_16x16x32_bf16 v[98:101], v[102:105], v[182:185], v[98:101]
	v_mfma_f32_16x16x32_bf16 v[76:79], v[80:83], v[196:199], v[76:79]
	v_mfma_f32_16x16x32_bf16 v[72:75], v[102:105], v[196:199], v[72:75]
	v_mfma_f32_16x16x32_bf16 v[142:145], v[88:91], v[164:167], v[142:145]
	v_mfma_f32_16x16x32_bf16 v[138:141], v[106:109], v[164:167], v[138:141]
	v_mfma_f32_16x16x32_bf16 v[126:129], v[88:91], v[172:175], v[126:129]
	v_mfma_f32_16x16x32_bf16 v[122:125], v[106:109], v[172:175], v[122:125]
	v_mfma_f32_16x16x32_bf16 v[110:113], v[88:91], v[186:189], v[110:113]
	v_mfma_f32_16x16x32_bf16 v[98:101], v[106:109], v[186:189], v[98:101]
	v_mfma_f32_16x16x32_bf16 v[76:79], v[88:91], v[200:203], v[76:79]
	v_mfma_f32_16x16x32_bf16 v[72:75], v[106:109], v[200:203], v[72:75]
	s_barrier
	s_setprio 0
	s_add_i32 s76, 0, 0x14000
	s_add_i32 s72, s72, s18
	v_add_u32_e32 v96, s76, v193
	v_lshl_add_u64 v[176:177], s[60:61], 0, v[150:151]
	s_mov_b32 m0, s72
	ds_read_b128 v[224:227], v96
	ds_read_b128 v[228:231], v96 offset:1024
	ds_read_b128 v[232:235], v96 offset:2048
	ds_read_b128 v[236:239], v96 offset:3072
	ds_read_b128 v[244:247], v195 offset:16384
	ds_read_b128 v[248:251], v195 offset:17408
	global_load_lds_dwordx4 v150, s[60:61]
	v_lshl_add_u64 v[190:191], s[60:61], 0, v[146:147]
	s_add_i32 m0, s72, 0x2000
	s_nop 0
	global_load_lds_dwordx4 v146, s[60:61]
	s_setprio 1
	s_barrier
	s_waitcnt lgkmcnt(0)
	v_mfma_f32_16x16x32_bf16 v[134:137], v[224:227], v[160:163], v[134:137]
	v_mfma_f32_16x16x32_bf16 v[130:133], v[232:235], v[160:163], v[130:133]
	v_mfma_f32_16x16x32_bf16 v[118:121], v[224:227], v[168:171], v[118:121]
	s_mov_b32 m0, s27
	v_mfma_f32_16x16x32_bf16 v[114:117], v[232:235], v[168:171], v[114:117]
	v_lshl_add_u64 v[240:241], s[62:63], 0, v[152:153]
	v_mfma_f32_16x16x32_bf16 v[92:95], v[224:227], v[182:185], v[92:95]
	v_mfma_f32_16x16x32_bf16 v[84:87], v[232:235], v[182:185], v[84:87]
	v_mfma_f32_16x16x32_bf16 v[68:71], v[224:227], v[196:199], v[68:71]
	v_mfma_f32_16x16x32_bf16 v[64:67], v[232:235], v[196:199], v[64:67]
	v_mfma_f32_16x16x32_bf16 v[134:137], v[228:231], v[164:167], v[134:137]
	v_mfma_f32_16x16x32_bf16 v[130:133], v[236:239], v[164:167], v[130:133]
	v_mfma_f32_16x16x32_bf16 v[118:121], v[228:231], v[172:175], v[118:121]
	v_mfma_f32_16x16x32_bf16 v[114:117], v[236:239], v[172:175], v[114:117]
	v_mfma_f32_16x16x32_bf16 v[92:95], v[228:231], v[186:189], v[92:95]
	v_mfma_f32_16x16x32_bf16 v[84:87], v[236:239], v[186:189], v[84:87]
	v_mfma_f32_16x16x32_bf16 v[68:71], v[228:231], v[200:203], v[68:71]
	v_mfma_f32_16x16x32_bf16 v[64:67], v[236:239], v[200:203], v[64:67]
	s_barrier
	s_setprio 0
	ds_read_b128 v[168:171], v195 offset:18432
	ds_read_b128 v[172:175], v195 offset:19456
	ds_read_b128 v[182:185], v195 offset:20480
	ds_read_b128 v[186:189], v195 offset:21504
	ds_read_b128 v[196:199], v195 offset:22528
	ds_read_b128 v[200:203], v195 offset:23552
	global_load_lds_dwordx4 v152, s[62:63]
	v_lshl_add_u64 v[242:243], s[62:63], 0, v[148:149]
	s_mov_b32 m0, s28
	s_nop 0
	global_load_lds_dwordx4 v148, s[62:63]
	s_waitcnt vmcnt(10)
	s_setprio 1
	s_barrier
	s_waitcnt lgkmcnt(0)
	v_mfma_f32_16x16x32_bf16 v[60:63], v[80:83], v[244:247], v[60:63]
	v_mfma_f32_16x16x32_bf16 v[56:59], v[102:105], v[244:247], v[56:59]
	v_mfma_f32_16x16x32_bf16 v[44:47], v[80:83], v[168:171], v[44:47]
	v_mfma_f32_16x16x32_bf16 v[40:43], v[102:105], v[168:171], v[40:43]
	v_mfma_f32_16x16x32_bf16 v[28:31], v[80:83], v[182:185], v[28:31]
	v_mfma_f32_16x16x32_bf16 v[24:27], v[102:105], v[182:185], v[24:27]
	v_mfma_f32_16x16x32_bf16 v[12:15], v[80:83], v[196:199], v[12:15]
	v_mfma_f32_16x16x32_bf16 v[8:11], v[102:105], v[196:199], v[8:11]
	v_mfma_f32_16x16x32_bf16 v[60:63], v[88:91], v[248:251], v[60:63]
	v_mfma_f32_16x16x32_bf16 v[56:59], v[106:109], v[248:251], v[56:59]
	v_mfma_f32_16x16x32_bf16 v[44:47], v[88:91], v[172:175], v[44:47]
	v_mfma_f32_16x16x32_bf16 v[40:43], v[106:109], v[172:175], v[40:43]
	v_mfma_f32_16x16x32_bf16 v[28:31], v[88:91], v[186:189], v[28:31]
	v_mfma_f32_16x16x32_bf16 v[24:27], v[106:109], v[186:189], v[24:27]
	v_mfma_f32_16x16x32_bf16 v[12:15], v[88:91], v[200:203], v[12:15]
	v_mfma_f32_16x16x32_bf16 v[8:11], v[106:109], v[200:203], v[8:11]
	s_barrier
	s_setprio 0
	v_add_u32_e32 v96, 0x18000, v193
	ds_read_b128 v[80:83], v96
	ds_read_b128 v[88:91], v96 offset:1024
	ds_read_b128 v[102:105], v96 offset:2048
	ds_read_b128 v[106:109], v96 offset:3072
	s_add_u32 s74, s60, 0x40000
	s_addc_u32 s75, s61, 0
	s_add_i32 s72, s76, s18
	s_mov_b32 m0, s72
	s_nop 0
	global_load_lds_dwordx4 v150, s[74:75]
	s_add_i32 m0, s72, 0x2000
	s_nop 0
	global_load_lds_dwordx4 v146, s[74:75]
	s_waitcnt vmcnt(6)
	s_setprio 1
	s_barrier
	v_mfma_f32_16x16x32_bf16 v[52:55], v[224:227], v[244:247], v[52:55]
	v_mfma_f32_16x16x32_bf16 v[48:51], v[232:235], v[244:247], v[48:51]
	v_mfma_f32_16x16x32_bf16 v[36:39], v[224:227], v[168:171], v[36:39]
	s_add_i32 s72, 0, 0x18000
	v_mfma_f32_16x16x32_bf16 v[32:35], v[232:235], v[168:171], v[32:35]
	v_add_u32_e32 v96, s72, v193
	v_mfma_f32_16x16x32_bf16 v[20:23], v[224:227], v[182:185], v[20:23]
	v_mfma_f32_16x16x32_bf16 v[16:19], v[232:235], v[182:185], v[16:19]
	v_mfma_f32_16x16x32_bf16 v[4:7], v[224:227], v[196:199], v[4:7]
	v_mfma_f32_16x16x32_bf16 v[0:3], v[232:235], v[196:199], v[0:3]
	v_mfma_f32_16x16x32_bf16 v[52:55], v[228:231], v[248:251], v[52:55]
	v_mfma_f32_16x16x32_bf16 v[48:51], v[236:239], v[248:251], v[48:51]
	v_mfma_f32_16x16x32_bf16 v[36:39], v[228:231], v[172:175], v[36:39]
	v_mfma_f32_16x16x32_bf16 v[32:35], v[236:239], v[172:175], v[32:35]
	v_mfma_f32_16x16x32_bf16 v[20:23], v[228:231], v[186:189], v[20:23]
	v_mfma_f32_16x16x32_bf16 v[16:19], v[236:239], v[186:189], v[16:19]
	v_mfma_f32_16x16x32_bf16 v[4:7], v[228:231], v[200:203], v[4:7]
	v_mfma_f32_16x16x32_bf16 v[0:3], v[236:239], v[200:203], v[0:3]
	s_barrier
	s_setprio 0
	s_add_u32 s62, s62, 0x40000
	s_addc_u32 s63, s63, 0
	s_mov_b32 m0, s37
	ds_read_b128 v[160:163], v195 offset:32768
	ds_read_b128 v[164:167], v195 offset:33792
	ds_read_b128 v[168:171], v195 offset:34816
	ds_read_b128 v[172:175], v195 offset:35840
	ds_read_b128 v[182:185], v195 offset:36864
	ds_read_b128 v[186:189], v195 offset:37888
	ds_read_b128 v[196:199], v195 offset:38912
	ds_read_b128 v[200:203], v195 offset:39936
	global_load_lds_dwordx4 v152, s[62:63]
	s_mov_b32 m0, s56
	s_nop 0
	global_load_lds_dwordx4 v148, s[62:63]
	s_setprio 1
	s_barrier
	s_waitcnt lgkmcnt(0)
	v_mfma_f32_16x16x32_bf16 v[142:145], v[80:83], v[160:163], v[142:145]
	v_mfma_f32_16x16x32_bf16 v[138:141], v[102:105], v[160:163], v[138:141]
	v_mfma_f32_16x16x32_bf16 v[126:129], v[80:83], v[168:171], v[126:129]
	v_mfma_f32_16x16x32_bf16 v[122:125], v[102:105], v[168:171], v[122:125]
	v_mfma_f32_16x16x32_bf16 v[110:113], v[80:83], v[182:185], v[110:113]
	v_mfma_f32_16x16x32_bf16 v[98:101], v[102:105], v[182:185], v[98:101]
	v_mfma_f32_16x16x32_bf16 v[76:79], v[80:83], v[196:199], v[76:79]
	v_mfma_f32_16x16x32_bf16 v[72:75], v[102:105], v[196:199], v[72:75]
	v_mfma_f32_16x16x32_bf16 v[142:145], v[88:91], v[164:167], v[142:145]
	v_mfma_f32_16x16x32_bf16 v[138:141], v[106:109], v[164:167], v[138:141]
	v_mfma_f32_16x16x32_bf16 v[126:129], v[88:91], v[172:175], v[126:129]
	v_mfma_f32_16x16x32_bf16 v[122:125], v[106:109], v[172:175], v[122:125]
	v_mfma_f32_16x16x32_bf16 v[110:113], v[88:91], v[186:189], v[110:113]
	v_mfma_f32_16x16x32_bf16 v[98:101], v[106:109], v[186:189], v[98:101]
	v_mfma_f32_16x16x32_bf16 v[76:79], v[88:91], v[200:203], v[76:79]
	v_mfma_f32_16x16x32_bf16 v[72:75], v[106:109], v[200:203], v[72:75]
	s_barrier
	s_setprio 0
	s_add_i32 s62, 0, 0x1c000
	s_add_i32 s63, s72, s18
	v_add_u32_e32 v96, s62, v193
	v_lshl_add_u64 v[176:177], v[176:177], 0, s[6:7]
	s_mov_b32 m0, s63
	ds_read_b128 v[224:227], v96
	ds_read_b128 v[228:231], v96 offset:1024
	ds_read_b128 v[232:235], v96 offset:2048
	ds_read_b128 v[236:239], v96 offset:3072
	ds_read_b128 v[244:247], v195 offset:49152
	ds_read_b128 v[248:251], v195 offset:50176
	global_load_lds_dwordx4 v[176:177], off
	v_lshl_add_u64 v[176:177], v[190:191], 0, s[6:7]
	s_add_i32 m0, s63, 0x2000
	s_nop 0
	global_load_lds_dwordx4 v[176:177], off
	s_setprio 1
	s_barrier
	s_waitcnt lgkmcnt(0)
	v_mfma_f32_16x16x32_bf16 v[134:137], v[224:227], v[160:163], v[134:137]
	v_mfma_f32_16x16x32_bf16 v[130:133], v[232:235], v[160:163], v[130:133]
	v_mfma_f32_16x16x32_bf16 v[118:121], v[224:227], v[168:171], v[118:121]
	s_mov_b32 m0, s64
	v_mfma_f32_16x16x32_bf16 v[114:117], v[232:235], v[168:171], v[114:117]
	v_lshl_add_u64 v[176:177], v[240:241], 0, s[6:7]
	v_mfma_f32_16x16x32_bf16 v[92:95], v[224:227], v[182:185], v[92:95]
	v_mfma_f32_16x16x32_bf16 v[84:87], v[232:235], v[182:185], v[84:87]
	v_mfma_f32_16x16x32_bf16 v[68:71], v[224:227], v[196:199], v[68:71]
	v_mfma_f32_16x16x32_bf16 v[64:67], v[232:235], v[196:199], v[64:67]
	v_mfma_f32_16x16x32_bf16 v[134:137], v[228:231], v[164:167], v[134:137]
	v_mfma_f32_16x16x32_bf16 v[130:133], v[236:239], v[164:167], v[130:133]
	v_mfma_f32_16x16x32_bf16 v[118:121], v[228:231], v[172:175], v[118:121]
	v_mfma_f32_16x16x32_bf16 v[114:117], v[236:239], v[172:175], v[114:117]
	v_mfma_f32_16x16x32_bf16 v[92:95], v[228:231], v[186:189], v[92:95]
	v_mfma_f32_16x16x32_bf16 v[84:87], v[236:239], v[186:189], v[84:87]
	v_mfma_f32_16x16x32_bf16 v[68:71], v[228:231], v[200:203], v[68:71]
	v_mfma_f32_16x16x32_bf16 v[64:67], v[236:239], v[200:203], v[64:67]
	s_barrier
	s_setprio 0
	ds_read_b128 v[168:171], v195 offset:51200
	ds_read_b128 v[172:175], v195 offset:52224
	ds_read_b128 v[182:185], v195 offset:53248
	ds_read_b128 v[186:189], v195 offset:54272
	ds_read_b128 v[196:199], v195 offset:55296
	ds_read_b128 v[200:203], v195 offset:56320
	global_load_lds_dwordx4 v[176:177], off
	v_lshl_add_u64 v[176:177], v[242:243], 0, s[6:7]
	s_mov_b32 m0, s65
	s_nop 0
	global_load_lds_dwordx4 v[176:177], off
	s_waitcnt vmcnt(10)
	s_setprio 1
	s_barrier
	s_waitcnt lgkmcnt(0)
	v_mfma_f32_16x16x32_bf16 v[60:63], v[80:83], v[244:247], v[60:63]
	v_mfma_f32_16x16x32_bf16 v[56:59], v[102:105], v[244:247], v[56:59]
	v_mfma_f32_16x16x32_bf16 v[44:47], v[80:83], v[168:171], v[44:47]
	v_mfma_f32_16x16x32_bf16 v[40:43], v[102:105], v[168:171], v[40:43]
	v_mfma_f32_16x16x32_bf16 v[28:31], v[80:83], v[182:185], v[28:31]
	v_mfma_f32_16x16x32_bf16 v[24:27], v[102:105], v[182:185], v[24:27]
	v_mfma_f32_16x16x32_bf16 v[12:15], v[80:83], v[196:199], v[12:15]
	v_mfma_f32_16x16x32_bf16 v[8:11], v[102:105], v[196:199], v[8:11]
	v_mfma_f32_16x16x32_bf16 v[60:63], v[88:91], v[248:251], v[60:63]
	v_mfma_f32_16x16x32_bf16 v[56:59], v[106:109], v[248:251], v[56:59]
	v_mfma_f32_16x16x32_bf16 v[44:47], v[88:91], v[172:175], v[44:47]
	v_mfma_f32_16x16x32_bf16 v[40:43], v[106:109], v[172:175], v[40:43]
	v_mfma_f32_16x16x32_bf16 v[28:31], v[88:91], v[186:189], v[28:31]
	v_mfma_f32_16x16x32_bf16 v[24:27], v[106:109], v[186:189], v[24:27]
	v_mfma_f32_16x16x32_bf16 v[12:15], v[88:91], v[200:203], v[12:15]
	v_mfma_f32_16x16x32_bf16 v[8:11], v[106:109], v[200:203], v[8:11]
	s_barrier
	s_setprio 0
	v_add_u32_e32 v96, 0x10000, v193
	ds_read_b128 v[80:83], v96
	ds_read_b128 v[88:91], v96 offset:1024
	ds_read_b128 v[102:105], v96 offset:2048
	ds_read_b128 v[106:109], v96 offset:3072
	s_add_u32 s60, s60, 0x40080
	s_addc_u32 s61, s61, 0
	s_add_i32 s62, s62, s18
	s_mov_b32 m0, s62
	s_nop 0
	global_load_lds_dwordx4 v150, s[60:61]
	s_add_i32 m0, s62, 0x2000
	s_nop 0
	global_load_lds_dwordx4 v146, s[60:61]
	s_waitcnt vmcnt(6)
	s_setprio 1
	s_barrier
	v_mfma_f32_16x16x32_bf16 v[52:55], v[224:227], v[244:247], v[52:55]
	v_mfma_f32_16x16x32_bf16 v[48:51], v[232:235], v[244:247], v[48:51]
	v_mfma_f32_16x16x32_bf16 v[36:39], v[224:227], v[168:171], v[36:39]
	s_add_i32 s71, s71, 2
	v_mfma_f32_16x16x32_bf16 v[32:35], v[232:235], v[168:171], v[32:35]
	s_add_u32 s58, s58, 0x100
	v_mfma_f32_16x16x32_bf16 v[20:23], v[224:227], v[182:185], v[20:23]
	s_addc_u32 s59, s59, 0
	v_mfma_f32_16x16x32_bf16 v[16:19], v[232:235], v[182:185], v[16:19]
	s_add_u32 s69, s69, 0x100
	v_mfma_f32_16x16x32_bf16 v[4:7], v[224:227], v[196:199], v[4:7]
	s_addc_u32 s70, s70, 0
	v_mfma_f32_16x16x32_bf16 v[0:3], v[232:235], v[196:199], v[0:3]
	s_cmp_gt_u32 s71, 13
	v_mfma_f32_16x16x32_bf16 v[52:55], v[228:231], v[248:251], v[52:55]
	v_mfma_f32_16x16x32_bf16 v[48:51], v[236:239], v[248:251], v[48:51]
	v_mfma_f32_16x16x32_bf16 v[36:39], v[228:231], v[172:175], v[36:39]
	v_mfma_f32_16x16x32_bf16 v[32:35], v[236:239], v[172:175], v[32:35]
	v_mfma_f32_16x16x32_bf16 v[20:23], v[228:231], v[186:189], v[20:23]
	v_mfma_f32_16x16x32_bf16 v[16:19], v[236:239], v[186:189], v[16:19]
	v_mfma_f32_16x16x32_bf16 v[4:7], v[228:231], v[200:203], v[4:7]
	v_mfma_f32_16x16x32_bf16 v[0:3], v[236:239], v[200:203], v[0:3]
	s_barrier
	s_setprio 0
	s_cbranch_scc0 .LBB0_557
	s_waitcnt lgkmcnt(0)
	s_lshl_b32 s47, s54, 8
	s_add_i32 s47, s47, s57
	v_or_b32_e32 v162, s47, v192
	v_ashrrev_i32_e32 v163, 31, v162
	v_or_b32_e32 v190, 16, v162
	v_lshlrev_b64 v[80:81], 6, v[162:163]
	v_ashrrev_i32_e32 v191, 31, v190
	v_or_b32_e32 v188, 32, v162
	v_lshl_add_u64 v[80:81], v[154:155], 0, v[80:81]
	v_lshlrev_b64 v[82:83], 6, v[190:191]
	v_ashrrev_i32_e32 v189, 31, v188
	v_lshl_add_u64 v[82:83], v[154:155], 0, v[82:83]
	global_load_dwordx4 v[174:177], v[80:81], off
	global_load_dwordx4 v[196:199], v[82:83], off
	v_lshlrev_b64 v[80:81], 6, v[188:189]
	v_or_b32_e32 v186, 48, v162
	v_lshl_add_u64 v[80:81], v[154:155], 0, v[80:81]
	v_ashrrev_i32_e32 v187, 31, v186
	global_load_dwordx4 v[200:203], v[80:81], off
	v_lshlrev_b64 v[80:81], 6, v[186:187]
	v_lshl_add_u64 v[80:81], v[154:155], 0, v[80:81]
	v_add_u32_e32 v184, 0x80, v162
	global_load_dwordx4 v[224:227], v[80:81], off
	v_ashrrev_i32_e32 v185, 31, v184
	v_lshlrev_b64 v[80:81], 6, v[184:185]
	v_lshl_add_u64 v[80:81], v[154:155], 0, v[80:81]
	global_load_dwordx4 v[228:231], v[80:81], off
	v_add_u32_e32 v172, 0x90, v162
	v_ashrrev_i32_e32 v173, 31, v172
	v_lshlrev_b64 v[80:81], 6, v[172:173]
	v_lshl_add_u64 v[80:81], v[154:155], 0, v[80:81]
	global_load_dwordx4 v[232:235], v[80:81], off
	v_add_u32_e32 v168, 0xa0, v162
	v_ashrrev_i32_e32 v169, 31, v168
	v_lshlrev_b64 v[80:81], 6, v[168:169]
	v_lshl_add_u64 v[80:81], v[154:155], 0, v[80:81]
	global_load_dwordx4 v[236:239], v[80:81], off
	v_add_u32_e32 v164, 0xb0, v162
	v_ashrrev_i32_e32 v165, 31, v164
	v_lshlrev_b64 v[80:81], 6, v[164:165]
	s_cmpk_lt_u32 s47, 0x2000
	v_lshl_add_u64 v[80:81], v[154:155], 0, v[80:81]
	s_cselect_b32 s47, 1, 2
	global_load_dwordx4 v[240:243], v[80:81], off
	v_mov_b32_e32 v218, s47
	v_cmp_lt_i32_e32 vcc, s23, v162
	v_lshl_or_b32 v166, s55, 8, v194
	v_ashrrev_i32_e32 v167, 31, v166
	v_cndmask_b32_e32 v185, 0, v218, vcc
	v_mul_u32_u24_e32 v82, 0x7600, v185
	v_lshlrev_b32_e32 v96, 2, v82
	v_lshl_add_u64 v[80:81], s[44:45], 0, v[96:97]
	v_lshl_add_u64 v[106:107], v[166:167], 2, v[80:81]
	global_load_dwordx4 v[80:83], v[106:107], off offset:16
	global_load_dwordx4 v[88:91], v[106:107], off
	global_load_dwordx4 v[102:105], v[106:107], off offset:528
	s_nop 0
	global_load_dwordx4 v[106:109], v[106:107], off offset:512
	v_lshl_or_b32 v160, s55, 7, v194
	v_cmp_lt_i32_e32 vcc, s23, v190
	s_waitcnt vmcnt(0)
	v_add_f32_e32 v96, v174, v175
	v_add_f32_e32 v161, v176, v177
	v_add_f32_e32 v96, v96, v161
	v_add_f32_e32 v161, v196, v197
	v_add_f32_e32 v163, v198, v199
	v_add_f32_e32 v161, v161, v163
	v_add_f32_e32 v165, v200, v201
	v_add_f32_e32 v169, v202, v203
	v_add_f32_e32 v163, v165, v169
	v_mov_b32_e32 v169, v161
	v_add_f32_e32 v170, v224, v225
	v_add_f32_e32 v171, v226, v227
	v_add_f32_e32 v165, v170, v171
	v_mov_b32_e32 v170, v163
	v_permlane16_swap_b32_e32 v161, v169
	s_nop 0
	v_permlane16_swap_b32_e32 v163, v170
	v_add_f32_e32 v201, v161, v169
	v_add_f32_e32 v199, v163, v170
	v_add_f32_e32 v161, v228, v229
	v_add_f32_e32 v163, v230, v231
	v_add_f32_e32 v161, v161, v163
	v_mov_b32_e32 v163, v161
	s_nop 1
	v_permlane16_swap_b32_e32 v161, v163
	v_add_f32_e32 v191, v161, v163
	v_add_f32_e32 v161, v232, v233
	v_add_f32_e32 v163, v234, v235
	v_add_f32_e32 v161, v161, v163
	v_mov_b32_e32 v173, v96
	v_mov_b32_e32 v163, v161
	s_nop 0
	v_permlane16_swap_b32_e32 v96, v173
	v_permlane16_swap_b32_e32 v161, v163
	v_add_f32_e32 v96, v96, v173
	v_add_f32_e32 v187, v161, v163
	v_add_f32_e32 v161, v236, v237
	v_add_f32_e32 v163, v238, v239
	v_mov_b32_e32 v173, v96
	v_add_f32_e32 v161, v161, v163
	s_nop 0
	v_permlane32_swap_b32_e32 v96, v173
	v_mov_b32_e32 v163, v161
	v_add_f32_e32 v96, v96, v173
	s_nop 0
	v_permlane16_swap_b32_e32 v161, v163
	v_fmamk_f32 v96, v96, 0x3a800000, v207
	v_add_f32_e32 v169, v161, v163
	v_add_f32_e32 v161, v240, v241
	v_add_f32_e32 v163, v242, v243
	v_mov_b32_e32 v171, v165
	v_rsq_f32_e32 v96, v96
	v_add_f32_e32 v161, v161, v163
	v_permlane16_swap_b32_e32 v165, v171
	v_mov_b32_e32 v163, v161
	v_add_f32_e32 v197, v165, v171
	s_nop 0
	v_permlane16_swap_b32_e32 v161, v163
	v_mov_b64_e32 v[170:171], s[42:43]
	v_add_f32_e32 v163, v161, v163
	v_ashrrev_i32_e32 v161, 31, v160
	v_mad_i64_i32 v[170:171], s[54:55], v162, s31, v[170:171]
	v_lshl_add_u64 v[224:225], v[160:161], 1, v[170:171]
	v_pk_mul_f32 v[182:183], v[82:83], s[0:1] op_sel_hi:[1,0]
	v_pk_mul_f32 v[176:177], v[80:81], s[0:1] op_sel_hi:[1,0]
	v_pk_mul_f32 v[174:175], v[90:91], s[0:1] op_sel_hi:[1,0]
	v_pk_mul_f32 v[170:171], v[88:89], s[0:1] op_sel_hi:[1,0]
	v_mul_f32_e32 v226, 0xbfb8aa3b, v96
	v_pk_fma_f32 v[228:229], v[144:145], v[226:227], v[174:175] op_sel_hi:[1,0,1]
	v_pk_fma_f32 v[230:231], v[142:143], v[226:227], v[170:171] op_sel_hi:[1,0,1]
	v_pk_fma_f32 v[232:233], v[140:141], v[226:227], v[182:183] op_sel_hi:[1,0,1]
	v_pk_fma_f32 v[226:227], v[138:139], v[226:227], v[176:177] op_sel_hi:[1,0,1]
	v_exp_f32_e32 v230, v230
	v_exp_f32_e32 v226, v226
	v_exp_f32_e32 v231, v231
	v_exp_f32_e32 v227, v227
	v_exp_f32_e32 v232, v232
	v_exp_f32_e32 v233, v233
	v_exp_f32_e32 v228, v228
	v_exp_f32_e32 v229, v229
	v_pk_add_f32 v[230:231], v[230:231], 1.0 op_sel_hi:[1,0]
	v_pk_add_f32 v[232:233], v[232:233], 1.0 op_sel_hi:[1,0]
	v_pk_add_f32 v[226:227], v[226:227], 1.0 op_sel_hi:[1,0]
	v_pk_add_f32 v[228:229], v[228:229], 1.0 op_sel_hi:[1,0]
	v_rcp_f32_e32 v230, v230
	v_rcp_f32_e32 v226, v226
	v_rcp_f32_e32 v231, v231
	v_rcp_f32_e32 v227, v227
	v_rcp_f32_e32 v232, v232
	v_rcp_f32_e32 v233, v233
	v_rcp_f32_e32 v228, v228
	v_rcp_f32_e32 v229, v229
	v_pk_fma_f32 v[142:143], v[142:143], v[96:97], v[88:89] op_sel_hi:[1,0,1]
	v_pk_fma_f32 v[140:141], v[140:141], v[96:97], v[82:83] op_sel_hi:[1,0,1]
	v_pk_fma_f32 v[138:139], v[138:139], v[96:97], v[80:81] op_sel_hi:[1,0,1]
	v_pk_fma_f32 v[134:135], v[134:135], v[96:97], v[106:107] op_sel_hi:[1,0,1]
	v_pk_fma_f32 v[132:133], v[132:133], v[96:97], v[104:105] op_sel_hi:[1,0,1]
	v_pk_fma_f32 v[130:131], v[130:131], v[96:97], v[102:103] op_sel_hi:[1,0,1]
	v_pk_fma_f32 v[144:145], v[144:145], v[96:97], v[90:91] op_sel_hi:[1,0,1]
	v_pk_fma_f32 v[136:137], v[136:137], v[96:97], v[108:109] op_sel_hi:[1,0,1]
	v_pk_mul_f32 v[134:135], v[142:143], v[134:135]
	v_pk_mul_f32 v[132:133], v[140:141], v[132:133]
	v_pk_mul_f32 v[130:131], v[138:139], v[130:131]
	v_pk_mul_f32 v[136:137], v[144:145], v[136:137]
	v_pk_mul_f32 v[134:135], v[134:135], v[230:231]
	v_pk_mul_f32 v[138:139], v[132:133], v[232:233]
	v_pk_mul_f32 v[132:133], v[130:131], v[226:227]
	v_cvt_pk_bf16_f32 v130, v134, v135
	v_mov_b32_e32 v202, v201
	v_mov_b32_e32 v200, v199
	v_mov_b32_e32 v198, v197
	v_mov_b32_e32 v196, v191
	v_mov_b32_e32 v189, v187
	v_mov_b32_e32 v173, v169
	v_mov_b32_e32 v165, v163
	v_pk_mul_f32 v[136:137], v[136:137], v[228:229]
	v_permlane32_swap_b32_e32 v201, v202
	v_cvt_pk_bf16_f32 v131, v136, v137
	v_cvt_pk_bf16_f32 v132, v132, v133
	v_cvt_pk_bf16_f32 v133, v138, v139
	global_store_dwordx4 v[224:225], v[130:133], off
	v_permlane32_swap_b32_e32 v199, v200
	s_nop 0
	v_cndmask_b32_e32 v130, 0, v218, vcc
	v_permlane32_swap_b32_e32 v197, v198
	v_permlane32_swap_b32_e32 v191, v196
	v_permlane32_swap_b32_e32 v187, v189
	v_permlane32_swap_b32_e32 v169, v173
	v_permlane32_swap_b32_e32 v163, v165
	v_cmp_ne_u32_e32 vcc, v130, v185
	s_and_saveexec_b64 s[54:55], vcc
	s_cbranch_execz .LBB0_560
	v_mul_u32_u24_e32 v80, 0x7600, v130
	v_lshlrev_b32_e32 v96, 2, v80
	v_lshl_add_u64 v[80:81], s[44:45], 0, v[96:97]
	v_lshl_add_u64 v[106:107], v[166:167], 2, v[80:81]
	global_load_dwordx4 v[88:91], v[106:107], off
	global_load_dwordx4 v[80:83], v[106:107], off offset:16
	global_load_dwordx4 v[102:105], v[106:107], off offset:528
	s_nop 0
	global_load_dwordx4 v[106:109], v[106:107], off offset:512
	v_mov_b32_e32 v185, v130
	s_waitcnt vmcnt(0)
	v_pk_mul_f32 v[170:171], v[88:89], s[0:1] op_sel_hi:[1,0]
	v_pk_mul_f32 v[174:175], v[90:91], s[0:1] op_sel_hi:[1,0]
	v_pk_mul_f32 v[176:177], v[80:81], s[0:1] op_sel_hi:[1,0]
	v_pk_mul_f32 v[182:183], v[82:83], s[0:1] op_sel_hi:[1,0]
